# passB: six of each unit's eight Q-tile requests issued ahead of the gate loads and scan so the two head-of-unit global latencies overlap; staging waits re-derived
# baseline (speedup 1.0000x reference)
; #define LAS __attribute__((address_space(3)))
; __device__ void passB_unit(const Params& p, LAS unsigned char* lds, int u, bool do_store = true) {
;     ...
;     const float* GL = (const float*)(p.ws + OFF_GL) + (size_t)b * 16 * 2048 + c * 128;
;     bf16_t* Qg = (bf16_t*)(p.ws + OFF_Q) + (size_t)((tokbase >> 8) * 4 + h) * 65536 + (c & 1) * 8 * 512;
;     const int sid0 = (b * 4 + h) * 2;
;     LAS float* wtot = lfA; LAS float* wmax = lfA + 8;
;     float sc_b = 0.f, sc_li = 0.f; int sc_t = 0;
;     if (tid < 256) { const int d = tid >> 7, i = tid & 127; sc_t = d ? 127 - i : i;
;         sc_li = GL[(size_t)(d * 8 + h) * 2048 + sc_t]; float inc = GL[(size_t)(d * 8 + 4 + h) * 2048 + sc_t];
; #pragma unroll
;         for (int off = 1; off < 64; off <<= 1) { const float n = __shfl_up(inc, off); inc += (lane >= off) ? n : 0.f; }
;         sc_b = inc; if (lane == 63) wtot[wid] = inc; }
;     { const int d = tid >> 8, k = tid & 255; nvec[tid] = ((const float*)(p.ws + OFF_NST))[(size_t)((sid0 + d) * 16 + c) * 256 + k]; }
; #pragma unroll
;     for (int i = 0; i < 8; ++i) { const int id = tid + 512 * i; const int w = id >> 9, m = (id >> 7) & 3, bj = (id >> 6) & 1, ln = id & 63;
;         *(LAS u32x4*)(Qs + ((w >> 2) * 64 + m * 16 + (ln & 15)) * 264 + bj * 128 + (w & 3) * 32 + (ln >> 4) * 8) = __builtin_nontemporal_load((const u32x4*)(Qg + (size_t)((w * 16 + m * 2 + bj) * 64 + ln) * 8)); }
.LBB0_533:
	s_lshl_b32 s0, s2, 1
	v_mov_b32_e32 v196, v224
	s_and_b32 s52, s0, 14
	s_movk_i32 s0, 0x100
	s_lshl_b32 s10, s52, 7
	v_ashrrev_i32_e32 v68, 6, v196
	v_and_b32_e32 v197, 63, v196
	v_cmp_gt_i32_e64 s[0:1], s0, v196
	v_mov_b32_e32 v63, 0
	v_mov_b32_e32 v69, 0
	v_mov_b32_e32 v0, 0
	v_readlane_b32 s60, v254, 24
	s_lshl_b32 s61, s60, 11
	s_or_b32 s61, s10, s61
	s_ashr_i32 s61, s61, 6
	s_or_b32 s62, s61, s34
	s_ashr_i32 s63, s62, 31
	s_lshl_b64 s[62:63], s[62:63], 17
	v_readlane_b32 s64, v254, 35
	v_readlane_b32 s65, v254, 36
	s_add_u32 s62, s64, s62
	s_addc_u32 s63, s65, s63
	v_bfe_u32 v34, v196, 7, 2
	v_bfe_u32 v198, v196, 6, 1
	v_lshlrev_b32_e32 v199, 1, v34
	v_add_u32_e32 v40, 0x400, v196
	v_ashrrev_i32_e32 v41, 9, v40
	v_lshlrev_b32_e32 v10, 4, v41
	v_or3_b32 v10, v199, v10, v198
	v_lshl_or_b32 v10, v10, 6, v197
	v_ashrrev_i32_e32 v11, 31, v10
	v_lshl_add_u64 v[10:11], v[10:11], 4, s[62:63]
	v_add_u32_e32 v42, 0x600, v196
	global_load_dwordx4 v[10:13], v[10:11], off nt
	v_ashrrev_i32_e32 v43, 9, v42
	v_lshlrev_b32_e32 v14, 4, v43
	v_or3_b32 v14, v199, v14, v198
	v_lshl_or_b32 v14, v14, 6, v197
	v_ashrrev_i32_e32 v15, 31, v14
	v_lshl_add_u64 v[14:15], v[14:15], 4, s[62:63]
	v_add_u32_e32 v44, 0x800, v196
	global_load_dwordx4 v[14:17], v[14:15], off nt
	v_ashrrev_i32_e32 v45, 9, v44
	v_lshlrev_b32_e32 v18, 4, v45
	v_or3_b32 v18, v199, v18, v198
	v_lshl_or_b32 v18, v18, 6, v197
	v_ashrrev_i32_e32 v19, 31, v18
	v_lshl_add_u64 v[18:19], v[18:19], 4, s[62:63]
	v_add_u32_e32 v46, 0xa00, v196
	global_load_dwordx4 v[18:21], v[18:19], off nt
	v_ashrrev_i32_e32 v47, 9, v46
	v_lshlrev_b32_e32 v22, 4, v47
	v_or3_b32 v22, v199, v22, v198
	v_lshl_or_b32 v22, v22, 6, v197
	v_ashrrev_i32_e32 v23, 31, v22
	v_lshl_add_u64 v[22:23], v[22:23], 4, s[62:63]
	v_add_u32_e32 v48, 0xc00, v196
	global_load_dwordx4 v[22:25], v[22:23], off nt
	v_ashrrev_i32_e32 v49, 9, v48
	v_lshlrev_b32_e32 v26, 4, v49
	v_or3_b32 v26, v199, v26, v198
	v_lshl_or_b32 v26, v26, 6, v197
	v_ashrrev_i32_e32 v27, 31, v26
	v_lshl_add_u64 v[26:27], v[26:27], 4, s[62:63]
	v_add_u32_e32 v50, 0xe00, v196
	global_load_dwordx4 v[26:29], v[26:27], off nt
	v_ashrrev_i32_e32 v51, 9, v50
	v_lshlrev_b32_e32 v30, 4, v51
	v_or3_b32 v30, v199, v30, v198
	v_lshl_or_b32 v30, v30, 6, v197
	v_ashrrev_i32_e32 v31, 31, v30
	v_lshl_add_u64 v[30:31], v[30:31], 4, s[62:63]
	global_load_dwordx4 v[30:33], v[30:31], off nt
	s_and_saveexec_b64 s[4:5], s[0:1]
	v_readlane_b32 s40, v254, 24
	v_readlane_b32 s41, v254, 25
	s_cbranch_execz .LBB0_537
	s_ashr_i32 s41, s40, 31
	s_lshl_b64 s[6:7], s[40:41], 17
	s_add_u32 s6, s70, s6
	s_addc_u32 s7, s71, s7
	s_lshl_b32 s11, s10, 2
	s_add_u32 s6, s6, s11
	s_movk_i32 s11, 0x7f
	s_movk_i32 s24, 0x80
	v_and_b32_e32 v0, 0x7f, v196
	v_bitop3_b32 v1, v196, s11, v196 bitop3:0xc
	v_cmp_gt_u32_e32 vcc, s24, v196
	s_addc_u32 s7, s7, 0
	s_add_u32 s6, s6, 0xfc00000
	v_cndmask_b32_e32 v63, v1, v0, vcc
	v_ashrrev_i32_e32 v0, 4, v196
	v_and_or_b32 v0, v0, -8, s34
	v_or_b32_e32 v4, 4, v0
	v_ashrrev_i32_e32 v5, 31, v4
	s_addc_u32 s7, s7, 0
	v_lshlrev_b64 v[4:5], 13, v[4:5]
	v_lshlrev_b32_e32 v2, 2, v63
	v_mov_b32_e32 v3, 0
	v_lshl_add_u64 v[4:5], s[6:7], 0, v[4:5]
	v_lshl_add_u64 v[4:5], v[4:5], 0, v[2:3]
	global_load_dword v4, v[4:5], off
	v_ashrrev_i32_e32 v1, 31, v0
	v_lshlrev_b64 v[0:1], 13, v[0:1]
	v_lshl_add_u64 v[0:1], s[6:7], 0, v[0:1]
	v_lshl_add_u64 v[0:1], v[0:1], 0, v[2:3]
	global_load_dword v0, v[0:1], off
	v_mbcnt_hi_u32_b32 v1, -1, v158
	v_and_b32_e32 v2, 64, v1
	v_add_u32_e32 v3, -1, v1
	v_cmp_lt_i32_e32 vcc, v3, v2
	v_add_u32_e32 v5, -2, v1
	v_add_u32_e32 v6, -4, v1
	v_cndmask_b32_e32 v3, v3, v1, vcc
	v_lshlrev_b32_e32 v3, 2, v3
	v_cmp_lt_i32_e32 vcc, v5, v2
	v_add_u32_e32 v7, -8, v1
	v_add_u32_e32 v8, -16, v1
	v_cndmask_b32_e32 v5, v5, v1, vcc
	v_cmp_ne_u32_e32 vcc, 0, v197
	v_lshlrev_b32_e32 v5, 2, v5
	v_subrev_u32_e32 v9, 32, v1
	s_waitcnt vmcnt(1)
	ds_bpermute_b32 v3, v3, v4
	s_waitcnt lgkmcnt(0)
	v_cndmask_b32_e32 v3, 0, v3, vcc
	v_add_f32_e32 v3, v4, v3
	ds_bpermute_b32 v4, v5, v3
	v_cmp_lt_i32_e32 vcc, v6, v2
	s_nop 1
	v_cndmask_b32_e32 v5, v6, v1, vcc
	v_cmp_lt_u32_e32 vcc, 1, v197
	v_lshlrev_b32_e32 v5, 2, v5
	s_waitcnt lgkmcnt(0)
	v_cndmask_b32_e32 v4, 0, v4, vcc
	v_add_f32_e32 v3, v3, v4
	ds_bpermute_b32 v4, v5, v3
	v_cmp_lt_i32_e32 vcc, v7, v2
	s_nop 1
	v_cndmask_b32_e32 v5, v7, v1, vcc
	v_cmp_lt_u32_e32 vcc, 3, v197
	v_lshlrev_b32_e32 v5, 2, v5
	s_waitcnt lgkmcnt(0)
	v_cndmask_b32_e32 v4, 0, v4, vcc
	v_add_f32_e32 v3, v3, v4
	ds_bpermute_b32 v4, v5, v3
	v_cmp_lt_i32_e32 vcc, v8, v2
	s_nop 1
	v_cndmask_b32_e32 v5, v8, v1, vcc
	v_cmp_lt_u32_e32 vcc, 7, v197
	v_lshlrev_b32_e32 v5, 2, v5
	s_waitcnt lgkmcnt(0)
	v_cndmask_b32_e32 v4, 0, v4, vcc
	v_add_f32_e32 v3, v3, v4
	ds_bpermute_b32 v4, v5, v3
	v_cmp_lt_i32_e32 vcc, v9, v2
	s_nop 1
	v_cndmask_b32_e32 v1, v9, v1, vcc
	v_cmp_lt_u32_e32 vcc, 15, v197
	v_lshlrev_b32_e32 v1, 2, v1
	s_waitcnt lgkmcnt(0)
	v_cndmask_b32_e32 v2, 0, v4, vcc
	v_add_f32_e32 v2, v3, v2
	ds_bpermute_b32 v1, v1, v2
	v_cmp_lt_u32_e32 vcc, 31, v197
	s_waitcnt lgkmcnt(0)
	s_nop 0
	v_cndmask_b32_e32 v1, 0, v1, vcc
	v_add_f32_e32 v69, v2, v1
	v_cmp_eq_u32_e32 vcc, 63, v197
	s_and_saveexec_b64 s[6:7], vcc
	v_lshl_add_u32 v1, v68, 2, 0
	v_add_u32_e32 v1, 0x21800, v1
	ds_write_b32 v1, v69
	s_or_b64 exec, exec, s[6:7]
; #define LAS __attribute__((address_space(3)))
; __device__ void passB_unit(const Params& p, LAS unsigned char* lds, int u, bool do_store = true) {
;     ...
;     { const int d = tid >> 8, k = tid & 255; nvec[tid] = ((const float*)(p.ws + OFF_NST))[(size_t)((sid0 + d) * 16 + c) * 256 + k]; }
; #pragma unroll
;     for (int i = 0; i < 8; ++i) { const int id = tid + 512 * i; const int w = id >> 9, m = (id >> 7) & 3, bj = (id >> 6) & 1, ln = id & 63;
;         *(LAS u32x4*)(Qs + ((w >> 2) * 64 + m * 16 + (ln & 15)) * 264 + bj * 128 + (w & 3) * 32 + (ln >> 4) * 8) = __builtin_nontemporal_load((const u32x4*)(Qg + (size_t)((w * 16 + m * 2 + bj) * 64 + ln) * 8)); }
.LBB0_537:
	s_or_b64 exec, exec, s[4:5]
	s_lshl_b32 s53, s40, 11
	s_or_b32 s4, s10, s53
	s_ashr_i32 s4, s4, 6
	s_or_b32 s4, s4, s34
	s_ashr_i32 s5, s4, 31
	s_lshl_b64 s[4:5], s[4:5], 17
	v_readlane_b32 s6, v254, 35
	v_readlane_b32 s7, v254, 36
	s_add_u32 s44, s6, s4
	s_addc_u32 s45, s7, s5
	s_lshl_b32 s4, s40, 3
	s_lshl_b32 s5, s34, 1
	s_or_b32 s50, s5, s4
	v_ashrrev_i32_e32 v62, 8, v196
	v_add_u32_e32 v1, s50, v62
	v_add_u32_e32 v38, 0x200, v196
	v_lshl_or_b32 v2, v1, 4, s52
	v_bfe_u32 v34, v196, 7, 2
	v_ashrrev_i32_e32 v39, 9, v38
	v_ashrrev_i32_e32 v3, 31, v2
	v_bfe_u32 v198, v196, 6, 1
	v_lshlrev_b32_e32 v199, 1, v34
	v_lshlrev_b32_e32 v6, 4, v39
	v_lshlrev_b64 v[2:3], 10, v[2:3]
	v_mov_b32_e32 v1, 2
	v_or3_b32 v6, v199, v6, v198
	v_lshl_add_u64 v[2:3], s[16:17], 0, v[2:3]
	v_lshlrev_b32_sdwa v60, v1, v196 dst_sel:DWORD dst_unused:UNUSED_PAD src0_sel:DWORD src1_sel:BYTE_0
	v_mov_b32_e32 v61, 0
	v_lshl_or_b32 v6, v6, 6, v197
	v_lshl_add_u64 v[2:3], v[2:3], 0, v[60:61]
	v_ashrrev_i32_e32 v7, 31, v6
	global_load_dword v1, v[2:3], off
	v_ashrrev_i32_e32 v35, 9, v196
	v_lshl_add_u64 v[6:7], v[6:7], 4, s[44:45]
	global_load_dwordx4 v[6:9], v[6:7], off nt
	v_lshlrev_b32_e32 v2, 4, v35
	v_or3_b32 v2, v199, v2, v198
	v_lshl_or_b32 v2, v2, 6, v197
	v_ashrrev_i32_e32 v3, 31, v2
	v_lshl_add_u64 v[2:3], v[2:3], 4, s[44:45]
	global_load_dwordx4 v[2:5], v[2:3], off nt
	v_lshl_add_u32 v92, v196, 2, 0
	v_lshrrev_b32_e32 v36, 1, v196
	v_add_u32_e32 v37, 0x23400, v92
	v_and_b32_e32 v201, 15, v196
	v_lshlrev_b32_e32 v202, 4, v34
	v_lshlrev_b32_e32 v203, 8, v198
	v_add_u32_e32 v34, 0, v203
	s_movk_i32 s6, 0x210
	v_and_b32_e32 v60, 64, v196
	v_mov_b32_e32 v70, v61
	s_waitcnt vmcnt(2)
	ds_write_b32 v37, v1
	v_and_b32_e32 v1, 24, v36
	v_ashrrev_i32_e32 v36, 5, v196
	v_and_b32_e32 v36, 0xfffffc0, v36
	v_or3_b32 v36, v36, v202, v201
	v_mad_u64_u32 v[36:37], s[4:5], v36, s6, v[34:35]
	v_lshlrev_b32_e32 v35, 6, v35
	v_and_b32_e32 v35, 0xc0, v35
	v_lshlrev_b32_e32 v200, 1, v1
	v_add3_u32 v1, v36, v35, v200
	s_waitcnt vmcnt(0)
	ds_write_b128 v1, v[2:5]
	v_ashrrev_i32_e32 v1, 5, v38
	v_and_b32_e32 v1, 0xfffffc0, v1
	v_or3_b32 v1, v202, v1, v201
	v_mad_u64_u32 v[2:3], s[4:5], v1, s6, v[34:35]
	v_lshlrev_b32_e32 v1, 6, v39
	v_and_b32_e32 v1, 0xc0, v1
	v_add3_u32 v1, v2, v1, v200
	ds_write_b128 v1, v[6:9]
	v_ashrrev_i32_e32 v1, 5, v40
	v_and_b32_e32 v1, 0xfffffc0, v1
	v_or3_b32 v1, v202, v1, v201
	v_mad_u64_u32 v[2:3], s[4:5], v1, s6, v[34:35]
	v_lshlrev_b32_e32 v1, 6, v41
	v_and_b32_e32 v1, 0xc0, v1
	v_add3_u32 v1, v2, v1, v200
	s_waitcnt vmcnt(5)
	ds_write_b128 v1, v[10:13]
	v_ashrrev_i32_e32 v1, 5, v42
	v_and_b32_e32 v1, 0xfffffc0, v1
	v_or3_b32 v1, v202, v1, v201
	v_mad_u64_u32 v[2:3], s[4:5], v1, s6, v[34:35]
	v_lshlrev_b32_e32 v1, 6, v43
	v_and_b32_e32 v1, 0xc0, v1
	v_add3_u32 v1, v2, v1, v200
	s_waitcnt vmcnt(4)
	ds_write_b128 v1, v[14:17]
	v_ashrrev_i32_e32 v1, 5, v44
	v_and_b32_e32 v1, 0xfffffc0, v1
	v_or3_b32 v1, v202, v1, v201
	v_mad_u64_u32 v[2:3], s[4:5], v1, s6, v[34:35]
	v_lshlrev_b32_e32 v1, 6, v45
	v_and_b32_e32 v1, 0xc0, v1
	v_add3_u32 v1, v2, v1, v200
	s_waitcnt vmcnt(3)
	ds_write_b128 v1, v[18:21]
	v_ashrrev_i32_e32 v1, 5, v46
	v_and_b32_e32 v1, 0xfffffc0, v1
	v_or3_b32 v1, v202, v1, v201
	v_mad_u64_u32 v[2:3], s[4:5], v1, s6, v[34:35]
	v_lshlrev_b32_e32 v1, 6, v47
	v_and_b32_e32 v1, 0xc0, v1
	v_add3_u32 v1, v2, v1, v200
	s_waitcnt vmcnt(2)
	ds_write_b128 v1, v[22:25]
	v_ashrrev_i32_e32 v1, 5, v48
	v_and_b32_e32 v1, 0xfffffc0, v1
	v_or3_b32 v1, v202, v1, v201
	v_mad_u64_u32 v[2:3], s[4:5], v1, s6, v[34:35]
	v_lshlrev_b32_e32 v1, 6, v49
	v_and_b32_e32 v1, 0xc0, v1
	v_add3_u32 v1, v2, v1, v200
	s_waitcnt vmcnt(1)
	ds_write_b128 v1, v[26:29]
	v_ashrrev_i32_e32 v1, 5, v50
	v_and_b32_e32 v1, 0xfffffc0, v1
	v_or3_b32 v1, v202, v1, v201
	v_mad_u64_u32 v[2:3], s[4:5], v1, s6, v[34:35]
	v_lshlrev_b32_e32 v1, 6, v51
	v_and_b32_e32 v1, 0xc0, v1
	v_add3_u32 v1, v2, v1, v200
	s_waitcnt vmcnt(0)
	ds_write_b128 v1, v[30:33]
	s_waitcnt lgkmcnt(0)
	s_barrier
	s_and_saveexec_b64 s[6:7], s[0:1]
	s_cbranch_execz .LBB0_543
	v_cmp_ne_u32_e32 vcc, 0, v60
	s_and_saveexec_b64 s[4:5], vcc
	s_cbranch_execz .LBB0_540
	v_lshlrev_b32_e32 v1, 2, v68
	s_add_i32 s10, 0, 0x21800
	v_add3_u32 v1, s10, v1, -4
	ds_read_b32 v1, v1
	s_waitcnt lgkmcnt(0)
	v_add_f32_e32 v69, v69, v1

; #define LAS __attribute__((address_space(3)))
; __device__ void passB_unit(const Params& p, LAS unsigned char* lds, int u, bool do_store = true) {
;     ...
;     if (tid < 256) { const int d = tid >> 7, i = tid & 127; sc_t = d ? 127 - i : i;
;         sc_li = GL[(size_t)(d * 8 + h) * 2048 + sc_t]; float inc = GL[(size_t)(d * 8 + 4 + h) * 2048 + sc_t];
; #pragma unroll
;         for (int off = 1; off < 64; off <<= 1) { const float n = __shfl_up(inc, off); inc += (lane >= off) ? n : 0.f; }
;         sc_b = inc; if (lane == 63) wtot[wid] = inc; }
;     { const int d = tid >> 8, k = tid & 255; nvec[tid] = ((const float*)(p.ws + OFF_NST))[(size_t)((sid0 + d) * 16 + c) * 256 + k]; }
; #pragma unroll
;     for (int i = 0; i < 8; ++i) { const int id = tid + 512 * i; const int w = id >> 9, m = (id >> 7) & 3, bj = (id >> 6) & 1, ln = id & 63;
;         *(LAS u32x4*)(Qs + ((w >> 2) * 64 + m * 16 + (ln & 15)) * 264 + bj * 128 + (w & 3) * 32 + (ln >> 4) * 8) = __builtin_nontemporal_load((const u32x4*)(Qg + (size_t)((w * 16 + m * 2 + bj) * 64 + ln) * 8)); }
;     ...
;     if (do_store) {
; #pragma unroll 2
;         for (int i = 0; i < 8; ++i) { const int id = tid + 512 * i; const int w = id >> 9, m = (id >> 7) & 3, bj = (id >> 6) & 1, ln = id & 63;
;             *(u32x4*)(Qg + (size_t)((w * 16 + m * 2 + bj) * 64 + ln) * 8) = *(const LAS u32x4*)(Pd + ((w >> 2) * 64 + m * 16 + (ln & 15)) * 264 + bj * 128 + (w & 3) * 32 + (ln >> 4) * 8); } }
.LBB0_568:
	v_add_u32_e32 v3, s0, v196
	v_ashrrev_i32_e32 v5, 5, v3
	v_ashrrev_i32_e32 v4, 9, v3
	v_add_u32_e32 v3, 0x200, v3
	v_and_or_b32 v5, v5, s1, v1
	v_lshlrev_b32_e32 v6, 6, v4
	v_lshlrev_b32_e32 v7, 10, v4
	v_ashrrev_i32_e32 v8, 9, v3
	v_ashrrev_i32_e32 v3, 5, v3
	v_mad_u64_u32 v[4:5], s[6:7], v5, s4, v[0:1]
	v_and_b32_e32 v5, 0xc0, v6
	v_and_or_b32 v3, v3, s1, v1
	v_lshlrev_b32_e32 v6, 6, v8
	v_or3_b32 v12, v7, v2, v197
	v_lshlrev_b32_e32 v7, 10, v8
	v_add3_u32 v8, v4, v5, v200
	v_mad_u64_u32 v[4:5], s[6:7], v3, s4, v[0:1]
	v_and_b32_e32 v3, 0xc0, v6
	v_or3_b32 v14, v7, v2, v197
	v_add3_u32 v3, v4, v3, v200
	ds_read_b128 v[4:7], v8
	ds_read_b128 v[8:11], v3
	s_addk_i32 s0, 0x400
	v_ashrrev_i32_e32 v13, 31, v12
	s_cmpk_lg_i32 s0, 0x1000
	v_lshl_add_u64 v[12:13], v[12:13], 4, s[44:45]
	v_ashrrev_i32_e32 v15, 31, v14
	v_lshl_add_u64 v[14:15], v[14:15], 4, s[44:45]
	s_waitcnt lgkmcnt(1)
	global_store_dwordx4 v[12:13], v[4:7], off
	s_waitcnt lgkmcnt(0)
	global_store_dwordx4 v[14:15], v[8:11], off
	s_cbranch_scc1 .LBB0_568
	v_mov_b32_e32 v196, v224
	s_or_b32 s24, s52, 1
	s_movk_i32 s0, 0x100
	s_barrier
	s_lshl_b32 s10, s24, 7
	v_ashrrev_i32_e32 v68, 6, v196
	v_and_b32_e32 v197, 63, v196
	v_cmp_gt_i32_e64 s[0:1], s0, v196
	v_mov_b32_e32 v63, 0
	v_mov_b32_e32 v69, 0
	v_add_u32_e32 v5, -1, v204
	v_add_u32_e32 v4, -2, v204
	v_add_u32_e32 v3, -4, v204
	v_add_u32_e32 v2, -8, v204
	v_add_u32_e32 v1, -16, v204
	v_subrev_u32_e32 v0, 32, v204
	v_mov_b32_e32 v6, 0
	s_or_b32 s61, s10, s53
	s_ashr_i32 s61, s61, 6
	s_and_b32 s61, s61, -4
	s_or_b32 s62, s61, s34
	s_ashr_i32 s63, s62, 31
	s_lshl_b64 s[62:63], s[62:63], 17
	v_readlane_b32 s64, v254, 35
	v_readlane_b32 s65, v254, 36
	s_add_u32 s62, s64, s62
	s_addc_u32 s63, s65, s63
	s_add_u32 s62, s62, 0x2000
	s_addc_u32 s63, s63, 0
	v_bfe_u32 v40, v196, 7, 2
	v_bfe_u32 v198, v196, 6, 1
	v_lshlrev_b32_e32 v199, 1, v40
	v_add_u32_e32 v46, 0x400, v196
	v_ashrrev_i32_e32 v47, 9, v46
	v_lshlrev_b32_e32 v16, 4, v47
	v_or3_b32 v16, v199, v16, v198
	v_lshl_or_b32 v16, v16, 6, v197
	v_ashrrev_i32_e32 v17, 31, v16
	v_lshl_add_u64 v[16:17], v[16:17], 4, s[62:63]
	v_add_u32_e32 v48, 0x600, v196
	global_load_dwordx4 v[16:19], v[16:17], off nt
	v_ashrrev_i32_e32 v49, 9, v48
	v_lshlrev_b32_e32 v20, 4, v49
	v_or3_b32 v20, v199, v20, v198
	v_lshl_or_b32 v20, v20, 6, v197
	v_ashrrev_i32_e32 v21, 31, v20
	v_lshl_add_u64 v[20:21], v[20:21], 4, s[62:63]
	v_add_u32_e32 v50, 0x800, v196
	global_load_dwordx4 v[20:23], v[20:21], off nt
	v_ashrrev_i32_e32 v51, 9, v50
	v_lshlrev_b32_e32 v24, 4, v51
	v_or3_b32 v24, v199, v24, v198
	v_lshl_or_b32 v24, v24, 6, v197
	v_ashrrev_i32_e32 v25, 31, v24
	v_lshl_add_u64 v[24:25], v[24:25], 4, s[62:63]
	v_add_u32_e32 v52, 0xa00, v196
	global_load_dwordx4 v[24:27], v[24:25], off nt
	v_ashrrev_i32_e32 v53, 9, v52
	v_lshlrev_b32_e32 v28, 4, v53
	v_or3_b32 v28, v199, v28, v198
	v_lshl_or_b32 v28, v28, 6, v197
	v_ashrrev_i32_e32 v29, 31, v28
	v_lshl_add_u64 v[28:29], v[28:29], 4, s[62:63]
	v_add_u32_e32 v54, 0xc00, v196
	global_load_dwordx4 v[28:31], v[28:29], off nt
	v_ashrrev_i32_e32 v55, 9, v54
	v_lshlrev_b32_e32 v32, 4, v55
	v_or3_b32 v32, v199, v32, v198
	v_lshl_or_b32 v32, v32, 6, v197
	v_ashrrev_i32_e32 v33, 31, v32
	v_lshl_add_u64 v[32:33], v[32:33], 4, s[62:63]
	v_add_u32_e32 v56, 0xe00, v196
	global_load_dwordx4 v[32:35], v[32:33], off nt
	v_ashrrev_i32_e32 v57, 9, v56
	v_lshlrev_b32_e32 v36, 4, v57
	v_or3_b32 v36, v199, v36, v198
	v_lshl_or_b32 v36, v36, 6, v197
	v_ashrrev_i32_e32 v37, 31, v36
	v_lshl_add_u64 v[36:37], v[36:37], 4, s[62:63]
	global_load_dwordx4 v[36:39], v[36:37], off nt
	s_and_saveexec_b64 s[4:5], s[0:1]
	s_cbranch_execz .LBB0_573
	s_ashr_i32 s41, s40, 31
	s_lshl_b64 s[6:7], s[40:41], 17
	s_add_u32 s6, s70, s6
	s_addc_u32 s7, s71, s7
	s_lshl_b32 s11, s10, 2
	s_add_u32 s6, s6, s11
	s_movk_i32 s11, 0x7f
	s_movk_i32 s25, 0x80
	v_and_b32_e32 v6, 0x7f, v196
	v_bitop3_b32 v7, v196, s11, v196 bitop3:0xc
	v_cmp_gt_u32_e32 vcc, s25, v196
	s_addc_u32 s7, s7, 0
	s_add_u32 s6, s6, 0xfc00000
	v_cndmask_b32_e32 v63, v7, v6, vcc
	v_ashrrev_i32_e32 v6, 4, v196
	v_and_or_b32 v6, v6, -8, s34
	v_or_b32_e32 v10, 4, v6
	v_ashrrev_i32_e32 v11, 31, v10
	s_addc_u32 s7, s7, 0
	v_lshlrev_b64 v[10:11], 13, v[10:11]
	v_lshlrev_b32_e32 v8, 2, v63
	v_mov_b32_e32 v9, 0
	v_lshl_add_u64 v[10:11], s[6:7], 0, v[10:11]
	v_lshl_add_u64 v[10:11], v[10:11], 0, v[8:9]
	global_load_dword v10, v[10:11], off
	v_ashrrev_i32_e32 v7, 31, v6
	v_lshlrev_b64 v[6:7], 13, v[6:7]
	v_lshl_add_u64 v[6:7], s[6:7], 0, v[6:7]
	v_lshl_add_u64 v[6:7], v[6:7], 0, v[8:9]
	global_load_dword v6, v[6:7], off
	v_cmp_lt_i32_e32 vcc, v5, v205
	s_nop 1
	v_cndmask_b32_e32 v7, v5, v204, vcc
	v_lshlrev_b32_e32 v7, 2, v7
	v_cmp_lt_i32_e32 vcc, v4, v205
	s_waitcnt vmcnt(1)
	ds_bpermute_b32 v7, v7, v10
	v_cndmask_b32_e32 v8, v4, v204, vcc
	v_cmp_ne_u32_e32 vcc, 0, v197
	v_lshlrev_b32_e32 v8, 2, v8
	s_waitcnt lgkmcnt(0)
	v_cndmask_b32_e32 v7, 0, v7, vcc
	v_add_f32_e32 v7, v10, v7
	ds_bpermute_b32 v8, v8, v7
	v_cmp_lt_i32_e32 vcc, v3, v205
	s_nop 1
	v_cndmask_b32_e32 v9, v3, v204, vcc
	v_cmp_lt_u32_e32 vcc, 1, v197
	v_lshlrev_b32_e32 v9, 2, v9
	s_waitcnt lgkmcnt(0)
	v_cndmask_b32_e32 v8, 0, v8, vcc
	v_add_f32_e32 v7, v7, v8
	ds_bpermute_b32 v8, v9, v7
	v_cmp_lt_i32_e32 vcc, v2, v205
	s_nop 1
	v_cndmask_b32_e32 v9, v2, v204, vcc
	v_cmp_lt_u32_e32 vcc, 3, v197
	v_lshlrev_b32_e32 v9, 2, v9
	s_waitcnt lgkmcnt(0)
	v_cndmask_b32_e32 v8, 0, v8, vcc
	v_add_f32_e32 v7, v7, v8
	ds_bpermute_b32 v8, v9, v7
	v_cmp_lt_i32_e32 vcc, v1, v205
	s_nop 1
	v_cndmask_b32_e32 v9, v1, v204, vcc
	v_cmp_lt_u32_e32 vcc, 7, v197
	v_lshlrev_b32_e32 v9, 2, v9
	s_waitcnt lgkmcnt(0)
	v_cndmask_b32_e32 v8, 0, v8, vcc
	v_add_f32_e32 v7, v7, v8
	ds_bpermute_b32 v8, v9, v7
	v_cmp_lt_i32_e32 vcc, v0, v205
	s_nop 1
	v_cndmask_b32_e32 v9, v0, v204, vcc
	v_cmp_lt_u32_e32 vcc, 15, v197
	v_lshlrev_b32_e32 v9, 2, v9
	s_waitcnt lgkmcnt(0)
	v_cndmask_b32_e32 v8, 0, v8, vcc
	v_add_f32_e32 v7, v7, v8
	ds_bpermute_b32 v8, v9, v7
	v_cmp_lt_u32_e32 vcc, 31, v197
	s_waitcnt lgkmcnt(0)
	s_nop 0
	v_cndmask_b32_e32 v8, 0, v8, vcc
	v_add_f32_e32 v69, v7, v8
	v_cmp_eq_u32_e32 vcc, 63, v197
	s_and_saveexec_b64 s[6:7], vcc
	v_lshl_add_u32 v7, v68, 2, 0
	v_add_u32_e32 v7, 0x21800, v7
	ds_write_b32 v7, v69
	s_or_b64 exec, exec, s[6:7]
; #define LAS __attribute__((address_space(3)))
; __device__ void passB_unit(const Params& p, LAS unsigned char* lds, int u, bool do_store = true) {
;     ...
;     { const int d = tid >> 8, k = tid & 255; nvec[tid] = ((const float*)(p.ws + OFF_NST))[(size_t)((sid0 + d) * 16 + c) * 256 + k]; }
; #pragma unroll
;     for (int i = 0; i < 8; ++i) { const int id = tid + 512 * i; const int w = id >> 9, m = (id >> 7) & 3, bj = (id >> 6) & 1, ln = id & 63;
;         *(LAS u32x4*)(Qs + ((w >> 2) * 64 + m * 16 + (ln & 15)) * 264 + bj * 128 + (w & 3) * 32 + (ln >> 4) * 8) = __builtin_nontemporal_load((const u32x4*)(Qg + (size_t)((w * 16 + m * 2 + bj) * 64 + ln) * 8)); }
.LBB0_573:
	s_or_b64 exec, exec, s[4:5]
	s_or_b32 s4, s10, s53
	s_ashr_i32 s4, s4, 6
	s_and_b32 s4, s4, -4
	s_or_b32 s4, s4, s34
	v_ashrrev_i32_e32 v62, 8, v196
	v_add_u32_e32 v7, s50, v62
	s_ashr_i32 s5, s4, 31
	v_add_u32_e32 v44, 0x200, v196
	v_lshl_or_b32 v8, v7, 4, s24
	s_lshl_b64 s[4:5], s[4:5], 17
	v_readlane_b32 s6, v254, 35
	v_bfe_u32 v40, v196, 7, 2
	v_ashrrev_i32_e32 v45, 9, v44
	v_ashrrev_i32_e32 v9, 31, v8
	v_readlane_b32 s7, v254, 36
	s_add_u32 s4, s6, s4
	v_bfe_u32 v198, v196, 6, 1
	v_lshlrev_b32_e32 v199, 1, v40
	v_lshlrev_b32_e32 v12, 4, v45
	v_lshlrev_b64 v[8:9], 10, v[8:9]
	v_mov_b32_e32 v7, 2
	s_addc_u32 s5, s7, s5
	v_or3_b32 v12, v199, v12, v198
	v_lshl_add_u64 v[8:9], s[16:17], 0, v[8:9]
	v_lshlrev_b32_sdwa v60, v7, v196 dst_sel:DWORD dst_unused:UNUSED_PAD src0_sel:DWORD src1_sel:BYTE_0
	v_mov_b32_e32 v61, 0
	s_add_u32 s16, s4, 0x2000
	v_lshl_or_b32 v12, v12, 6, v197
	v_lshl_add_u64 v[8:9], v[8:9], 0, v[60:61]
	s_addc_u32 s17, s5, 0
	v_ashrrev_i32_e32 v13, 31, v12
	global_load_dword v7, v[8:9], off
	v_ashrrev_i32_e32 v41, 9, v196
	v_lshl_add_u64 v[12:13], v[12:13], 4, s[16:17]
	global_load_dwordx4 v[12:15], v[12:13], off nt
	v_lshlrev_b32_e32 v8, 4, v41
	v_or3_b32 v8, v199, v8, v198
	v_lshl_or_b32 v8, v8, 6, v197
	v_ashrrev_i32_e32 v9, 31, v8
	v_lshl_add_u64 v[8:9], v[8:9], 4, s[16:17]
	global_load_dwordx4 v[8:11], v[8:9], off nt
	v_lshl_add_u32 v92, v196, 2, 0
	v_add_u32_e32 v42, 0x23400, v92
	v_and_b32_e32 v201, 15, v196
	v_lshlrev_b32_e32 v202, 4, v40
	v_lshlrev_b32_e32 v203, 8, v198
	v_add_u32_e32 v40, 0, v203
	s_movk_i32 s6, 0x210
	v_and_b32_e32 v60, 64, v196
	v_mov_b32_e32 v70, v61
	s_waitcnt vmcnt(2)
	ds_write_b32 v42, v7
	v_ashrrev_i32_e32 v42, 5, v196
	v_and_b32_e32 v42, 0xfffffc0, v42
	v_lshrrev_b32_e32 v7, 1, v196
	v_or3_b32 v42, v42, v202, v201
	v_and_b32_e32 v7, 24, v7
	v_mad_u64_u32 v[42:43], s[4:5], v42, s6, v[40:41]
	v_lshlrev_b32_e32 v41, 6, v41
	v_and_b32_e32 v41, 0xc0, v41
	v_lshlrev_b32_e32 v200, 1, v7
	v_add3_u32 v7, v42, v41, v200
	s_waitcnt vmcnt(0)
	ds_write_b128 v7, v[8:11]
	v_ashrrev_i32_e32 v7, 5, v44
	v_and_b32_e32 v7, 0xfffffc0, v7
	v_or3_b32 v7, v202, v7, v201
	v_mad_u64_u32 v[8:9], s[4:5], v7, s6, v[40:41]
	v_lshlrev_b32_e32 v7, 6, v45
	v_and_b32_e32 v7, 0xc0, v7
	v_add3_u32 v7, v8, v7, v200
	ds_write_b128 v7, v[12:15]
	v_ashrrev_i32_e32 v7, 5, v46
	v_and_b32_e32 v7, 0xfffffc0, v7
	v_or3_b32 v7, v202, v7, v201
	v_mad_u64_u32 v[8:9], s[4:5], v7, s6, v[40:41]
	v_lshlrev_b32_e32 v7, 6, v47
	v_and_b32_e32 v7, 0xc0, v7
	v_add3_u32 v7, v8, v7, v200
	s_waitcnt vmcnt(5)
	ds_write_b128 v7, v[16:19]
	v_ashrrev_i32_e32 v7, 5, v48
	v_and_b32_e32 v7, 0xfffffc0, v7
	v_or3_b32 v7, v202, v7, v201
	v_mad_u64_u32 v[8:9], s[4:5], v7, s6, v[40:41]
	v_lshlrev_b32_e32 v7, 6, v49
	v_and_b32_e32 v7, 0xc0, v7
	v_add3_u32 v7, v8, v7, v200
	s_waitcnt vmcnt(4)
	ds_write_b128 v7, v[20:23]
	v_ashrrev_i32_e32 v7, 5, v50
	v_and_b32_e32 v7, 0xfffffc0, v7
	v_or3_b32 v7, v202, v7, v201
	v_mad_u64_u32 v[8:9], s[4:5], v7, s6, v[40:41]
	v_lshlrev_b32_e32 v7, 6, v51
	v_and_b32_e32 v7, 0xc0, v7
	v_add3_u32 v7, v8, v7, v200
	s_waitcnt vmcnt(3)
	ds_write_b128 v7, v[24:27]
	v_ashrrev_i32_e32 v7, 5, v52
	v_and_b32_e32 v7, 0xfffffc0, v7
	v_or3_b32 v7, v202, v7, v201
	v_mad_u64_u32 v[8:9], s[4:5], v7, s6, v[40:41]
	v_lshlrev_b32_e32 v7, 6, v53
	v_and_b32_e32 v7, 0xc0, v7
	v_add3_u32 v7, v8, v7, v200
	s_waitcnt vmcnt(2)
	ds_write_b128 v7, v[28:31]
	v_ashrrev_i32_e32 v7, 5, v54
	v_and_b32_e32 v7, 0xfffffc0, v7
	v_or3_b32 v7, v202, v7, v201
	v_mad_u64_u32 v[8:9], s[4:5], v7, s6, v[40:41]
	v_lshlrev_b32_e32 v7, 6, v55
	v_and_b32_e32 v7, 0xc0, v7
	v_add3_u32 v7, v8, v7, v200
	s_waitcnt vmcnt(1)
	ds_write_b128 v7, v[32:35]
	v_ashrrev_i32_e32 v7, 5, v56
	v_and_b32_e32 v7, 0xfffffc0, v7
	v_or3_b32 v7, v202, v7, v201
	v_mad_u64_u32 v[8:9], s[4:5], v7, s6, v[40:41]
	v_lshlrev_b32_e32 v7, 6, v57
	v_and_b32_e32 v7, 0xc0, v7
	v_add3_u32 v7, v8, v7, v200
	s_waitcnt vmcnt(0)
	ds_write_b128 v7, v[36:39]
	s_waitcnt lgkmcnt(0)
	s_barrier
	s_and_saveexec_b64 s[6:7], s[0:1]
	s_cbranch_execz .LBB0_579
	v_cmp_ne_u32_e32 vcc, 0, v60
	s_and_saveexec_b64 s[4:5], vcc
	s_cbranch_execz .LBB0_576
	v_lshlrev_b32_e32 v7, 2, v68
	s_add_i32 s10, 0, 0x21800
	v_add3_u32 v7, s10, v7, -4
	ds_read_b32 v7, v7
	s_waitcnt lgkmcnt(0)
	v_add_f32_e32 v69, v69, v7

; #define PG8_STAGE(bufoff, gbase, voff) do { _Pragma("unroll") for (int _i = 0; _i < 2; ++_i) \
;         __builtin_amdgcn_global_load_lds((const unsigned*)((const char*)(gbase) + (voff)[_i]), (LAS unsigned*)(lds + (bufoff) + ldsw + _i * 8192), 16, 0, 0); } while (0)
; #define PG8_WAIT_V(n) asm volatile("s_waitcnt vmcnt(" #n ")" ::: "memory")
; #define PG8_BAR __builtin_amdgcn_s_barrier()
;     __device__ __forceinline__ bool next(int i, Unit& u) const { if (i == 0) { u.pm = pm; u.pn = pn; return true; } return false; }
; template <class Epi, class Sched, bool ZERO>
; __device__ __forceinline__ void gemm_phase_acc(LAS unsigned char* lds, const Gemm g, const Sched& S, const Epi& E, f32x4 (&acc)[2][2][4][2]) {
;     ...
;     Unit cur, nxt; int ui = 0;
;     if (!S.next(0, cur)) return;
;     if constexpr (ZERO) {
; #pragma unroll
;     for (int a = 0; a < 2; ++a)
; #pragma unroll
;         for (int b = 0; b < 2; ++b)
; #pragma unroll
;             for (int m = 0; m < 4; ++m)
; #pragma unroll
;                 for (int n = 0; n < 2; ++n) acc[a][b][m][n] = (f32x4){0.f, 0.f, 0.f, 0.f};
;     }
;     bf16x8 At[4][2], B0[2][2], B1[2][2];
;     const char* cA = (const char*)g.A + (size_t)cur.pm * tstep; const char* cB = (const char*)g.Bt + (size_t)cur.pn * tstep;
;     PG8_STAGE(PG8_SB(0, 0), cB, voffB); PG8_STAGE(PG8_SA(0, 0), cA, voffA); PG8_STAGE(PG8_SB(0, 1), cB + hstep, voffB); PG8_STAGE(PG8_SA(0, 1), cA + hstep, voffA);
;     if (wr == 1) PG8_BAR;
;     PG8_WAIT_V(4); PG8_BAR;
;     PG8_STAGE(PG8_SB(1, 0), cB + kstep, voffB); PG8_STAGE(PG8_SA(1, 0), cA + kstep, voffA); PG8_STAGE(PG8_SB(1, 1), cB + hstep + kstep, voffB);
;     PG8_WAIT_V(6); PG8_BAR;
.LBB0_630:
	v_and_b32_e32 v15, 15, v13
	v_bfe_u32 v16, v13, 4, 2
	s_and_b32 s17, s3, 3
	v_lshl_or_b32 v85, s4, 6, v15
	v_lshlrev_b32_e32 v84, 4, v16
	s_lshl_b32 s3, s4, 13
	v_lshlrev_b32_e32 v13, 2, v13
	s_mov_b64 s[4:5], 0x80
	v_lshl_or_b32 v15, v15, 6, v84
	v_and_b32_e32 v13, 32, v13
	s_add_i32 m0, s11, 0x18000
	v_lshl_add_u64 v[6:7], v[6:7], 0, s[4:5]
	v_bitop3_b32 v16, v15, s3, v13 bitop3:0xde
	s_lshl_b32 s3, s17, 12
	s_waitcnt vmcnt(4)
	s_barrier
	global_load_lds_dwordx4 v[6:7], off
	v_lshl_add_u64 v[4:5], v[4:5], 0, s[4:5]
	s_add_i32 m0, s11, 0x1a000
	s_add_i32 s24, s11, 0x8000
	s_add_i32 s25, s11, 0xa000
	global_load_lds_dwordx4 v[4:5], off
	v_lshl_add_u64 v[2:3], v[2:3], 0, s[4:5]
	s_mov_b32 m0, s24
	s_add_u32 s26, s0, 0x40080
	global_load_lds_dwordx4 v[2:3], off
	v_lshl_add_u64 v[0:1], v[0:1], 0, s[4:5]
	s_mov_b32 m0, s25
	s_addc_u32 s27, s1, 0
	global_load_lds_dwordx4 v[0:1], off
	s_add_i32 m0, s11, 0x1c000
	v_lshl_add_u64 v[0:1], s[26:27], 0, v[50:51]
	global_load_lds_dwordx4 v[0:1], off
	v_lshl_add_u64 v[0:1], s[26:27], 0, v[62:63]
	s_add_i32 m0, s11, 0x1e000
	v_readlane_b32 s26, v254, 26
	global_load_lds_dwordx4 v[0:1], off
	v_lshlrev_b32_e32 v0, 14, v8
	v_and_b32_e32 v0, 0xffff8000, v0
	v_lshl_add_u32 v0, v9, 11, v0
	v_and_b32_e32 v1, 1, v8
	v_lshl_or_b32 v0, v1, 6, v0
	v_readlane_b32 s27, v254, 27
	s_add_u32 s26, s70, s26
	v_lshl_add_u32 v0, v10, 1, v0
	v_mov_b32_e32 v1, v51
	s_addc_u32 s27, s71, s27
	s_mov_b64 s[8:9], 0x40080
	v_lshl_add_u64 v[0:1], s[26:27], 0, v[0:1]
	v_lshl_add_u64 v[72:73], v[0:1], 0, s[8:9]
	v_lshlrev_b32_e32 v0, 14, v11
	v_and_b32_e32 v0, 0xffff8000, v0
	s_lshl_b32 s2, s2, 16
	v_lshl_add_u32 v0, v12, 11, v0
	v_and_b32_e32 v1, 1, v11
	s_and_b32 s2, s2, 0x180000
	v_lshl_or_b32 v0, v1, 6, v0
	s_add_u32 s2, s70, s2
	v_bitop3_b32 v13, v15, s3, v13 bitop3:0xde
	v_lshl_add_u32 v0, v14, 1, v0
	v_mov_b32_e32 v1, v51
	s_addc_u32 s3, s71, 0
	s_waitcnt vmcnt(6)
	v_lshl_add_u64 v[0:1], s[26:27], 0, v[0:1]
	s_add_u32 s26, s2, 0x2e00100
	s_addc_u32 s27, s3, 0
	s_add_i32 s31, s35, s6
	s_add_i32 s39, s22, s6
	s_add_i32 s41, s23, s6
	s_add_i32 s43, s33, s6
	v_lshl_add_u64 v[74:75], v[0:1], 0, s[8:9]
	s_mov_b32 s28, -2
	s_mov_b64 s[2:3], 0
	v_add_u32_e32 v86, s35, v13
	v_add_u32_e32 v87, 0, v16
	s_add_i32 s29, s11, 0xc000
	s_add_i32 s30, s11, 0xe000
	v_add_u32_e32 v88, s22, v13
	s_add_i32 s38, s31, 0x2000
	s_add_i32 s40, s39, 0x2000
	v_add_u32_e32 v89, s23, v13
	v_add_u32_e32 v90, s33, v13
	s_add_i32 s42, s41, 0x2000
	s_add_i32 s44, s43, 0x2000
	v_mov_b32_e32 v0, v51
	v_mov_b32_e32 v1, v51
	v_mov_b32_e32 v2, v51
	v_mov_b32_e32 v3, v51
	v_mov_b32_e32 v4, v51
	v_mov_b32_e32 v5, v51
	v_mov_b32_e32 v6, v51
	v_mov_b32_e32 v7, v51
	v_mov_b32_e32 v16, v51
	v_mov_b32_e32 v17, v51
	v_mov_b32_e32 v18, v51
	v_mov_b32_e32 v19, v51
	v_mov_b32_e32 v20, v51
	v_mov_b32_e32 v21, v51
	v_mov_b32_e32 v22, v51
	v_mov_b32_e32 v23, v51
	v_mov_b32_e32 v32, v51
	v_mov_b32_e32 v33, v51
	v_mov_b32_e32 v34, v51
	v_mov_b32_e32 v35, v51
	v_mov_b32_e32 v36, v51
	v_mov_b32_e32 v37, v51
	v_mov_b32_e32 v38, v51
	v_mov_b32_e32 v39, v51
	v_mov_b32_e32 v52, v51
	v_mov_b32_e32 v53, v51
	v_mov_b32_e32 v54, v51
	v_mov_b32_e32 v55, v51
	v_mov_b32_e32 v56, v51
	v_mov_b32_e32 v57, v51
	v_mov_b32_e32 v58, v51
	v_mov_b32_e32 v59, v51
	v_mov_b32_e32 v8, v51
	v_mov_b32_e32 v9, v51
	v_mov_b32_e32 v10, v51
	v_mov_b32_e32 v11, v51
	v_mov_b32_e32 v12, v51
	v_mov_b32_e32 v13, v51
	v_mov_b32_e32 v14, v51
	v_mov_b32_e32 v15, v51
	v_mov_b32_e32 v24, v51
	v_mov_b32_e32 v25, v51
	v_mov_b32_e32 v26, v51
	v_mov_b32_e32 v27, v51
	v_mov_b32_e32 v28, v51
	v_mov_b32_e32 v29, v51
	v_mov_b32_e32 v30, v51
	v_mov_b32_e32 v31, v51
	v_mov_b32_e32 v40, v51
	v_mov_b32_e32 v41, v51
	v_mov_b32_e32 v42, v51
	v_mov_b32_e32 v43, v51
	v_mov_b32_e32 v44, v51
	v_mov_b32_e32 v45, v51
	v_mov_b32_e32 v46, v51
	v_mov_b32_e32 v47, v51
	v_mov_b32_e32 v64, v51
	v_mov_b32_e32 v65, v51
	v_mov_b32_e32 v66, v51
	v_mov_b32_e32 v67, v51
	v_mov_b32_e32 v68, v51
	v_mov_b32_e32 v69, v51
	v_mov_b32_e32 v70, v51
	v_mov_b32_e32 v71, v51
	v_mov_b32_e32 v76, v51
	v_mov_b32_e32 v77, v51
	v_mov_b32_e32 v78, v51
	v_mov_b32_e32 v79, v51
	v_mov_b32_e32 v80, v51
	v_mov_b32_e32 v81, v51
	v_mov_b32_e32 v82, v51
	v_mov_b32_e32 v83, v51
	v_mov_b32_e32 v104, v51
	v_mov_b32_e32 v105, v51
	v_mov_b32_e32 v106, v51
	v_mov_b32_e32 v107, v51
	v_mov_b32_e32 v108, v51
	v_mov_b32_e32 v109, v51
	v_mov_b32_e32 v110, v51
	v_mov_b32_e32 v111, v51
	v_mov_b32_e32 v128, v51
	v_mov_b32_e32 v129, v51
	v_mov_b32_e32 v130, v51
	v_mov_b32_e32 v131, v51
	v_mov_b32_e32 v132, v51
	v_mov_b32_e32 v133, v51
	v_mov_b32_e32 v134, v51
	v_mov_b32_e32 v135, v51
	v_mov_b32_e32 v144, v51
	v_mov_b32_e32 v145, v51
	v_mov_b32_e32 v146, v51
	v_mov_b32_e32 v147, v51
	v_mov_b32_e32 v148, v51
	v_mov_b32_e32 v149, v51
	v_mov_b32_e32 v150, v51
	v_mov_b32_e32 v151, v51
	v_mov_b32_e32 v92, v51
	v_mov_b32_e32 v93, v51
	v_mov_b32_e32 v94, v51
	v_mov_b32_e32 v95, v51
	v_mov_b32_e32 v96, v51
	v_mov_b32_e32 v97, v51
	v_mov_b32_e32 v98, v51
	v_mov_b32_e32 v99, v51
	v_mov_b32_e32 v116, v51
	v_mov_b32_e32 v117, v51
	v_mov_b32_e32 v118, v51
	v_mov_b32_e32 v119, v51
	v_mov_b32_e32 v120, v51
	v_mov_b32_e32 v121, v51
	v_mov_b32_e32 v122, v51
	v_mov_b32_e32 v123, v51
	v_mov_b32_e32 v136, v51
	v_mov_b32_e32 v137, v51
	v_mov_b32_e32 v138, v51
	v_mov_b32_e32 v139, v51
	v_mov_b32_e32 v140, v51
	v_mov_b32_e32 v141, v51
	v_mov_b32_e32 v142, v51
	v_mov_b32_e32 v143, v51
	v_mov_b32_e32 v152, v51
	v_mov_b32_e32 v153, v51
	v_mov_b32_e32 v154, v51
	v_mov_b32_e32 v155, v51
	v_mov_b32_e32 v156, v51
	v_mov_b32_e32 v157, v51
	v_mov_b32_e32 v158, v51
	v_mov_b32_e32 v159, v51
	s_barrier
	s_nop 0
	s_nop 0
